# M1H: residual (mode-1) epilogue loads the first three tiles of the second row half together with the first half, ahead of its write-through stores in the in-order vmcnt queue, on top of v074
# baseline (speedup 1.0000x reference)
.LBB0_205:
	s_nop 0
	v_mbcnt_hi_u32_b32 v130, -1, v227
	v_and_b32_e32 v132, 64, v130
	s_waitcnt lgkmcnt(0)
	v_xor_b32_e32 v131, 16, v130
	v_add_u32_e32 v132, 64, v132
	v_cmp_lt_i32_e32 vcc, v131, v132
	v_ashrrev_i32_e32 v199, 31, v198
	v_lshlrev_b32_e32 v170, 1, v206
	v_cndmask_b32_e32 v131, v130, v131, vcc
	v_lshlrev_b32_e32 v168, 2, v131
	v_xor_b32_e32 v131, 32, v130
	v_cmp_lt_i32_e32 vcc, v131, v132
	v_readlane_b32 s76, v248, 38
	v_lshl_add_u32 v171, v198, 11, v170
	v_cndmask_b32_e32 v130, v130, v131, vcc
	v_lshlrev_b32_e32 v169, 2, v130
	v_lshlrev_b64 v[130:131], 11, v[198:199]
	v_lshl_add_u64 v[130:131], v[166:167], 0, v[130:131]
	global_load_dwordx4 v[172:175], v[130:131], off
	global_load_dwordx4 v[154:157], v[130:131], off offset:64
	v_lshlrev_b64 v[130:131], 11, v[204:205]
	v_lshl_add_u64 v[130:131], v[166:167], 0, v[130:131]
	global_load_dwordx4 v[150:153], v[130:131], off
	global_load_dwordx4 v[146:149], v[130:131], off offset:64
	v_lshlrev_b64 v[130:131], 11, v[202:203]
	v_lshl_add_u64 v[130:131], v[166:167], 0, v[130:131]
	global_load_dwordx4 v[142:145], v[130:131], off
	global_load_dwordx4 v[138:141], v[130:131], off offset:64
	v_lshlrev_b64 v[130:131], 11, v[200:201]
	v_lshl_add_u64 v[130:131], v[166:167], 0, v[130:131]
	global_load_dwordx4 v[134:137], v[130:131], off
	s_nop 0
	global_load_dwordx4 v[130:133], v[130:131], off offset:64
	v_lshlrev_b64 v[218:219], 11, v[164:165]
	v_lshl_add_u64 v[218:219], v[166:167], 0, v[218:219]
	global_load_dwordx4 v[210:213], v[218:219], off
	global_load_dwordx4 v[214:217], v[218:219], off offset:64
	v_lshlrev_b64 v[218:219], 11, v[162:163]
	v_lshl_add_u64 v[218:219], v[166:167], 0, v[218:219]
	global_load_dwordx4 v[244:247], v[218:219], off
	v_readlane_b32 s77, v248, 39
	v_readlane_b32 s78, v248, 40
	v_readlane_b32 s79, v248, 41
	v_readlane_b32 s0, v243, 44
	v_readlane_b32 s1, v243, 45
	s_waitcnt vmcnt(0)
	v_lshlrev_b32_e32 v176, 16, v172
	v_and_b32_e32 v177, 0xffff0000, v172
	v_lshlrev_b32_e32 v172, 16, v173
	v_and_b32_e32 v173, 0xffff0000, v173
	v_lshlrev_b32_e32 v178, 16, v174
	v_and_b32_e32 v179, 0xffff0000, v174
	v_lshlrev_b32_e32 v174, 16, v175
	v_and_b32_e32 v175, 0xffff0000, v175
	v_pk_fma_f32 v[176:177], s[58:59], v[126:127], v[176:177]
	v_pk_fma_f32 v[180:181], s[58:59], v[128:129], v[172:173]
	v_pk_fma_f32 v[178:179], s[58:59], v[122:123], v[178:179]
	v_pk_fma_f32 v[182:183], s[58:59], v[124:125], v[174:175]
	v_cvt_pk_bf16_f32 v172, v176, v177
	v_cvt_pk_bf16_f32 v173, v180, v181
	v_cvt_pk_bf16_f32 v174, v178, v179
	v_cvt_pk_bf16_f32 v175, v182, v183
	buffer_store_dwordx4 v[172:175], v171, s[76:79], 0 offen sc1
	v_lshlrev_b32_e32 v176, 16, v172
	v_lshlrev_b32_e32 v177, 16, v173
	v_and_b32_e32 v172, 0xffff0000, v172
	v_mul_f32_e32 v180, v172, v172
	v_fmac_f32_e32 v180, v176, v176
	v_and_b32_e32 v173, 0xffff0000, v173
	v_fmac_f32_e32 v180, v177, v177
	v_lshlrev_b32_e32 v178, 16, v174
	v_fmac_f32_e32 v180, v173, v173
	v_and_b32_e32 v174, 0xffff0000, v174
	v_fmac_f32_e32 v180, v178, v178
	v_lshlrev_b32_e32 v179, 16, v175
	v_fmac_f32_e32 v180, v174, v174
	v_and_b32_e32 v175, 0xffff0000, v175
	v_fmac_f32_e32 v180, v179, v179
	v_fmac_f32_e32 v180, v175, v175
	v_lshlrev_b32_e32 v172, 16, v154
	v_and_b32_e32 v173, 0xffff0000, v154
	v_lshlrev_b32_e32 v154, 16, v155
	v_and_b32_e32 v155, 0xffff0000, v155
	v_lshlrev_b32_e32 v174, 16, v156
	v_and_b32_e32 v175, 0xffff0000, v156
	v_lshlrev_b32_e32 v156, 16, v157
	v_and_b32_e32 v157, 0xffff0000, v157
	v_pk_fma_f32 v[172:173], s[58:59], v[114:115], v[172:173]
	v_pk_fma_f32 v[176:177], s[58:59], v[116:117], v[154:155]
	v_pk_fma_f32 v[174:175], s[58:59], v[110:111], v[174:175]
	v_pk_fma_f32 v[178:179], s[58:59], v[112:113], v[156:157]
	v_cvt_pk_bf16_f32 v154, v172, v173
	v_cvt_pk_bf16_f32 v155, v176, v177
	v_cvt_pk_bf16_f32 v156, v174, v175
	v_cvt_pk_bf16_f32 v157, v178, v179
	buffer_store_dwordx4 v[154:157], v171, s[76:79], 0 offen offset:64 sc1
	v_lshlrev_b32_e32 v171, 16, v154
	v_lshlrev_b32_e32 v172, 16, v155
	v_and_b32_e32 v154, 0xffff0000, v154
	v_mul_f32_e32 v154, v154, v154
	v_fmac_f32_e32 v154, v171, v171
	v_and_b32_e32 v155, 0xffff0000, v155
	v_fmac_f32_e32 v154, v172, v172
	v_lshlrev_b32_e32 v173, 16, v156
	v_fmac_f32_e32 v154, v155, v155
	v_and_b32_e32 v156, 0xffff0000, v156
	v_fmac_f32_e32 v154, v173, v173
	v_lshlrev_b32_e32 v174, 16, v157
	v_fmac_f32_e32 v154, v156, v156
	v_and_b32_e32 v157, 0xffff0000, v157
	v_fmac_f32_e32 v154, v174, v174
	v_fmac_f32_e32 v154, v157, v157
	v_add_f32_e32 v154, v180, v154
	ds_bpermute_b32 v155, v168, v154
	s_waitcnt lgkmcnt(0)
	v_add_f32_e32 v156, v154, v155
	ds_bpermute_b32 v157, v169, v156
	v_lshl_add_u64 v[154:155], v[198:199], 2, s[0:1]
	s_and_saveexec_b64 s[34:35], s[38:39]
	s_cbranch_execz .LBB0_207
	s_waitcnt lgkmcnt(0)
	v_add_f32_e32 v156, v156, v157
	global_atomic_add_f32 v[154:155], v156, off

.LBB0_213:
	s_or_b64 exec, exec, s[34:35]
	s_waitcnt lgkmcnt(0)
	v_mov_b32_e32 v172, v210
	v_mov_b32_e32 v173, v211
	v_mov_b32_e32 v174, v212
	v_mov_b32_e32 v175, v213
	v_mov_b32_e32 v176, v214
	v_mov_b32_e32 v177, v215
	v_mov_b32_e32 v178, v216
	v_mov_b32_e32 v179, v217
	v_mov_b32_e32 v150, v244
	v_mov_b32_e32 v151, v245
	v_mov_b32_e32 v152, v246
	v_mov_b32_e32 v153, v247
	v_lshlrev_b64 v[130:131], 11, v[162:163]
	v_lshl_add_u64 v[130:131], v[166:167], 0, v[130:131]
	global_load_dwordx4 v[146:149], v[130:131], off offset:64
	v_lshlrev_b64 v[130:131], 11, v[160:161]
	v_lshl_add_u64 v[130:131], v[166:167], 0, v[130:131]
	global_load_dwordx4 v[142:145], v[130:131], off
	global_load_dwordx4 v[138:141], v[130:131], off offset:64
	v_lshlrev_b64 v[130:131], 11, v[158:159]
	v_lshl_add_u64 v[130:131], v[166:167], 0, v[130:131]
	global_load_dwordx4 v[134:137], v[130:131], off
	s_nop 0
	global_load_dwordx4 v[130:133], v[130:131], off offset:64
	v_lshl_add_u32 v159, v164, 11, v170
	v_readlane_b32 s76, v248, 38
	v_readlane_b32 s77, v248, 39
	v_readlane_b32 s78, v248, 40
	v_readlane_b32 s79, v248, 41
	v_lshlrev_b32_e32 v156, 16, v172
	v_and_b32_e32 v157, 0xffff0000, v172
	v_lshlrev_b32_e32 v164, 16, v173
	v_and_b32_e32 v165, 0xffff0000, v173
	v_pk_fma_f32 v[156:157], s[58:59], v[62:63], v[156:157]
	v_lshlrev_b32_e32 v166, 16, v174
	v_and_b32_e32 v167, 0xffff0000, v174
	v_lshlrev_b32_e32 v172, 16, v175
	v_and_b32_e32 v173, 0xffff0000, v175
	v_pk_fma_f32 v[174:175], s[58:59], v[64:65], v[164:165]
	v_cvt_pk_bf16_f32 v164, v156, v157
	v_and_b32_e32 v157, 0xffff0000, v164
	v_cvt_pk_bf16_f32 v165, v174, v175
	v_lshlrev_b32_e32 v156, 16, v164
	v_mul_f32_e32 v171, v157, v157
	v_pk_fma_f32 v[166:167], s[58:59], v[58:59], v[166:167]
	v_pk_fma_f32 v[172:173], s[58:59], v[60:61], v[172:173]
	v_lshlrev_b32_e32 v161, 16, v165
	v_fmac_f32_e32 v171, v156, v156
	v_cvt_pk_bf16_f32 v166, v166, v167
	v_cvt_pk_bf16_f32 v167, v172, v173
	v_and_b32_e32 v163, 0xffff0000, v165
	v_fmac_f32_e32 v171, v161, v161
	buffer_store_dwordx4 v[164:167], v159, s[76:79], 0 offen sc1
	v_fmac_f32_e32 v171, v163, v163
	v_lshlrev_b32_e32 v156, 16, v176
	v_lshlrev_b32_e32 v164, 16, v166
	v_and_b32_e32 v165, 0xffff0000, v166
	v_fmac_f32_e32 v171, v164, v164
	v_lshlrev_b32_e32 v166, 16, v167
	v_fmac_f32_e32 v171, v165, v165
	v_and_b32_e32 v157, 0xffff0000, v176
	v_and_b32_e32 v167, 0xffff0000, v167
	v_fmac_f32_e32 v171, v166, v166
	v_lshlrev_b32_e32 v164, 16, v177
	v_and_b32_e32 v165, 0xffff0000, v177
	v_pk_fma_f32 v[156:157], s[58:59], v[54:55], v[156:157]
	v_fmac_f32_e32 v171, v167, v167
	v_lshlrev_b32_e32 v166, 16, v178
	v_and_b32_e32 v167, 0xffff0000, v178
	v_lshlrev_b32_e32 v172, 16, v179
	v_and_b32_e32 v173, 0xffff0000, v179
	v_pk_fma_f32 v[174:175], s[58:59], v[56:57], v[164:165]
	v_cvt_pk_bf16_f32 v164, v156, v157
	v_pk_fma_f32 v[166:167], s[58:59], v[50:51], v[166:167]
	v_pk_fma_f32 v[172:173], s[58:59], v[52:53], v[172:173]
	v_and_b32_e32 v157, 0xffff0000, v164
	v_cvt_pk_bf16_f32 v165, v174, v175
	v_cvt_pk_bf16_f32 v166, v166, v167
	v_cvt_pk_bf16_f32 v167, v172, v173
	v_lshlrev_b32_e32 v156, 16, v164
	v_mul_f32_e32 v157, v157, v157
	buffer_store_dwordx4 v[164:167], v159, s[76:79], 0 offen offset:64 sc1
	v_lshlrev_b32_e32 v159, 16, v165
	v_fmac_f32_e32 v157, v156, v156
	v_and_b32_e32 v161, 0xffff0000, v165
	v_fmac_f32_e32 v157, v159, v159
	v_lshlrev_b32_e32 v163, 16, v166
	v_fmac_f32_e32 v157, v161, v161
	v_and_b32_e32 v164, 0xffff0000, v166
	v_fmac_f32_e32 v157, v163, v163
	v_lshlrev_b32_e32 v165, 16, v167
	v_fmac_f32_e32 v157, v164, v164
	v_and_b32_e32 v166, 0xffff0000, v167
	v_fmac_f32_e32 v157, v165, v165
	v_fmac_f32_e32 v157, v166, v166
	v_add_f32_e32 v156, v171, v157
	ds_bpermute_b32 v157, v168, v156
	s_waitcnt lgkmcnt(0)
	v_add_f32_e32 v156, v156, v157
	ds_bpermute_b32 v157, v169, v156
	s_and_saveexec_b64 s[34:35], s[38:39]
	s_cbranch_execz .LBB0_215
	s_waitcnt lgkmcnt(0)
	v_add_f32_e32 v156, v156, v157
	global_atomic_add_f32 v[154:155], v156, off offset:512
.LBB0_215:
	s_or_b64 exec, exec, s[34:35]
	v_lshl_add_u32 v159, v162, 11, v170
	v_lshlrev_b32_e32 v156, 16, v150
	s_waitcnt lgkmcnt(0)
	v_and_b32_e32 v157, 0xffff0000, v150
	v_lshlrev_b32_e32 v150, 16, v151
	v_and_b32_e32 v151, 0xffff0000, v151
	v_lshlrev_b32_e32 v162, 16, v152
	v_and_b32_e32 v163, 0xffff0000, v152
	v_lshlrev_b32_e32 v152, 16, v153
	v_and_b32_e32 v153, 0xffff0000, v153
	v_pk_fma_f32 v[156:157], s[58:59], v[46:47], v[156:157]
	v_pk_fma_f32 v[164:165], s[58:59], v[48:49], v[150:151]
	v_pk_fma_f32 v[162:163], s[58:59], v[42:43], v[162:163]
	v_pk_fma_f32 v[166:167], s[58:59], v[44:45], v[152:153]
	v_readlane_b32 s76, v248, 38
	v_cvt_pk_bf16_f32 v150, v156, v157
	v_cvt_pk_bf16_f32 v151, v164, v165
	v_cvt_pk_bf16_f32 v152, v162, v163
	v_cvt_pk_bf16_f32 v153, v166, v167
	v_readlane_b32 s77, v248, 39
	v_readlane_b32 s78, v248, 40
	v_readlane_b32 s79, v248, 41
	v_lshlrev_b32_e32 v156, 16, v150
	v_lshlrev_b32_e32 v157, 16, v151
	v_lshlrev_b32_e32 v161, 16, v152
	v_lshlrev_b32_e32 v162, 16, v153
	s_nop 0
	buffer_store_dwordx4 v[150:153], v159, s[76:79], 0 offen sc1
	s_nop 1
	v_and_b32_e32 v150, 0xffff0000, v150
	v_mul_f32_e32 v164, v150, v150
	v_fmac_f32_e32 v164, v156, v156
	v_and_b32_e32 v151, 0xffff0000, v151
	v_fmac_f32_e32 v164, v157, v157
	v_fmac_f32_e32 v164, v151, v151
	v_and_b32_e32 v152, 0xffff0000, v152
	v_fmac_f32_e32 v164, v161, v161
	v_fmac_f32_e32 v164, v152, v152
	v_and_b32_e32 v153, 0xffff0000, v153
	v_fmac_f32_e32 v164, v162, v162
	v_fmac_f32_e32 v164, v153, v153
	s_waitcnt vmcnt(7)
	v_lshlrev_b32_e32 v150, 16, v146
	v_and_b32_e32 v151, 0xffff0000, v146
	v_lshlrev_b32_e32 v146, 16, v147
	v_and_b32_e32 v147, 0xffff0000, v147
	v_lshlrev_b32_e32 v152, 16, v148
	v_and_b32_e32 v153, 0xffff0000, v148
	v_lshlrev_b32_e32 v148, 16, v149
	v_and_b32_e32 v149, 0xffff0000, v149
	v_pk_fma_f32 v[150:151], s[58:59], v[38:39], v[150:151]
	v_pk_fma_f32 v[156:157], s[58:59], v[40:41], v[146:147]
	v_pk_fma_f32 v[152:153], s[58:59], v[34:35], v[152:153]
	v_pk_fma_f32 v[162:163], s[58:59], v[36:37], v[148:149]
	v_cvt_pk_bf16_f32 v146, v150, v151
	v_cvt_pk_bf16_f32 v147, v156, v157
	v_cvt_pk_bf16_f32 v148, v152, v153
	v_cvt_pk_bf16_f32 v149, v162, v163
	buffer_store_dwordx4 v[146:149], v159, s[76:79], 0 offen offset:64 sc1
	v_lshlrev_b32_e32 v150, 16, v146
	v_lshlrev_b32_e32 v151, 16, v147
	v_and_b32_e32 v146, 0xffff0000, v146
	v_mul_f32_e32 v146, v146, v146
	v_fmac_f32_e32 v146, v150, v150
	v_and_b32_e32 v147, 0xffff0000, v147
	v_fmac_f32_e32 v146, v151, v151
	v_lshlrev_b32_e32 v152, 16, v148
	v_fmac_f32_e32 v146, v147, v147
	v_and_b32_e32 v148, 0xffff0000, v148
	v_fmac_f32_e32 v146, v152, v152
	v_lshlrev_b32_e32 v153, 16, v149
	v_fmac_f32_e32 v146, v148, v148
	v_and_b32_e32 v149, 0xffff0000, v149
	v_fmac_f32_e32 v146, v153, v153
	v_fmac_f32_e32 v146, v149, v149
	v_add_f32_e32 v146, v164, v146
	ds_bpermute_b32 v147, v168, v146
	s_waitcnt lgkmcnt(0)
	v_add_f32_e32 v146, v146, v147
	ds_bpermute_b32 v147, v169, v146
	s_and_saveexec_b64 s[34:35], s[38:39]
	s_cbranch_execz .LBB0_217
	s_waitcnt lgkmcnt(0)
	v_add_f32_e32 v146, v146, v147
	global_atomic_add_f32 v[154:155], v146, off offset:576
